# v88 + MLP-up epilogue: the eight rstd LDS reads hoisted to the top (one exposed LDS latency per tile)
# baseline (speedup 1.0000x reference)
.LBB0_1200:
	v_lshl_add_u32 v147, s5, 10, v142
	ds_read_b32 v150, v147
	ds_read_b32 v152, v147 offset:64
	ds_read_b32 v154, v147 offset:128
	ds_read_b32 v156, v147 offset:192
	ds_read_b32 v158, v147 offset:512
	ds_read_b32 v160, v147 offset:576
	ds_read_b32 v162, v147 offset:640
	ds_read_b32 v164, v147 offset:704
	v_lshl_or_b32 v145, s6, 9, v143
	s_lshl_b32 s5, s7, 21
	v_add3_u32 v145, s5, v141, v145
	s_andn2_b64 vcc, exec, s[40:41]
	s_waitcnt lgkmcnt(0)
	v_pk_mul_f32 v[122:123], v[122:123], v[150:151] op_sel_hi:[1,0]
	v_pk_mul_f32 v[126:127], v[126:127], v[150:151] op_sel_hi:[1,0]
	v_pk_mul_f32 v[124:125], v[124:125], v[150:151] op_sel_hi:[1,0]
	v_max_f32_e32 v122, 0, v122
	v_pk_mul_f32 v[128:129], v[128:129], v[150:151] op_sel_hi:[1,0]
	v_mul_f32_e32 v148, v122, v122
	v_max_f32_e32 v122, 0, v127
	v_max_f32_e32 v123, 0, v123
	v_max_f32_e32 v124, 0, v124
	v_max_f32_e32 v126, 0, v126
	v_mul_f32_e32 v122, v122, v122
	v_mul_f32_e32 v127, v123, v123
	v_max_f32_e32 v123, 0, v128
	v_mul_f32_e32 v128, v124, v124
	v_max_f32_e32 v124, 0, v129
	v_max_f32_e32 v125, 0, v125
	v_pk_mul_f32 v[116:117], v[116:117], v[150:151] op_sel_hi:[1,0]
	v_pk_mul_f32 v[114:115], v[114:115], v[150:151] op_sel_hi:[1,0]
	v_mul_f32_e32 v126, v126, v126
	v_mul_f32_e32 v123, v123, v123
	v_mul_f32_e32 v124, v124, v124
	v_mul_f32_e32 v125, v125, v125
	v_cvt_pk_bf16_f32 v122, v126, v122
	v_pk_mul_f32 v[120:121], v[120:121], v[150:151] op_sel_hi:[1,0]
	v_pk_mul_f32 v[118:119], v[118:119], v[150:151] op_sel_hi:[1,0]
	v_max_f32_e32 v114, 0, v114
	v_max_f32_e32 v115, 0, v115
	v_max_f32_e32 v116, 0, v116
	v_cvt_pk_bf16_f32 v123, v123, v124
	v_cvt_pk_bf16_f32 v124, v148, v127
	v_cvt_pk_bf16_f32 v125, v128, v125
	global_store_dwordx4 v145, v[122:125], s[42:43]
	v_max_f32_e32 v118, 0, v118
	v_max_f32_e32 v117, 0, v117
	v_mul_f32_e32 v122, v114, v114
	v_max_f32_e32 v114, 0, v119
	v_mul_f32_e32 v119, v115, v115
	v_max_f32_e32 v115, 0, v120
	v_mul_f32_e32 v120, v116, v116
	v_max_f32_e32 v116, 0, v121
	v_mul_f32_e32 v118, v118, v118
	v_mul_f32_e32 v114, v114, v114
	v_mul_f32_e32 v115, v115, v115
	v_mul_f32_e32 v116, v116, v116
	v_mul_f32_e32 v117, v117, v117
	v_cvt_pk_bf16_f32 v114, v118, v114
	v_cvt_pk_bf16_f32 v115, v115, v116
	v_cvt_pk_bf16_f32 v116, v122, v119
	v_cvt_pk_bf16_f32 v117, v120, v117
	v_or_b32_e32 v119, 0x100, v145
	global_store_dwordx4 v119, v[114:117], s[42:43]
	s_mov_b64 s[40:41], -1
	s_waitcnt lgkmcnt(0)
	v_pk_mul_f32 v[106:107], v[106:107], v[152:153] op_sel_hi:[1,0]
	v_pk_mul_f32 v[110:111], v[110:111], v[152:153] op_sel_hi:[1,0]
	v_pk_mul_f32 v[108:109], v[108:109], v[152:153] op_sel_hi:[1,0]
	v_max_f32_e32 v106, 0, v106
	v_pk_mul_f32 v[112:113], v[112:113], v[152:153] op_sel_hi:[1,0]
	v_mul_f32_e32 v115, v106, v106
	v_max_f32_e32 v106, 0, v111
	v_max_f32_e32 v107, 0, v107
	v_max_f32_e32 v108, 0, v108
	v_max_f32_e32 v110, 0, v110
	v_mul_f32_e32 v106, v106, v106
	v_mul_f32_e32 v111, v107, v107
	v_max_f32_e32 v107, 0, v112
	v_mul_f32_e32 v112, v108, v108
	v_max_f32_e32 v108, 0, v113
	v_max_f32_e32 v109, 0, v109
	v_pk_mul_f32 v[100:101], v[100:101], v[152:153] op_sel_hi:[1,0]
	v_pk_mul_f32 v[98:99], v[98:99], v[152:153] op_sel_hi:[1,0]
	v_add_u32_e32 v114, 0x20000, v145
	v_mul_f32_e32 v110, v110, v110
	v_mul_f32_e32 v107, v107, v107
	v_mul_f32_e32 v108, v108, v108
	v_mul_f32_e32 v109, v109, v109
	v_cvt_pk_bf16_f32 v106, v110, v106
	v_pk_mul_f32 v[104:105], v[104:105], v[152:153] op_sel_hi:[1,0]
	v_pk_mul_f32 v[102:103], v[102:103], v[152:153] op_sel_hi:[1,0]
	v_max_f32_e32 v98, 0, v98
	v_max_f32_e32 v99, 0, v99
	v_max_f32_e32 v100, 0, v100
	v_cvt_pk_bf16_f32 v107, v107, v108
	v_cvt_pk_bf16_f32 v108, v115, v111
	v_cvt_pk_bf16_f32 v109, v112, v109
	global_store_dwordx4 v114, v[106:109], s[42:43]
	v_max_f32_e32 v102, 0, v102
	v_max_f32_e32 v101, 0, v101
	v_mul_f32_e32 v106, v98, v98
	v_max_f32_e32 v98, 0, v103
	v_mul_f32_e32 v103, v99, v99
	v_max_f32_e32 v99, 0, v104
	v_mul_f32_e32 v104, v100, v100
	v_max_f32_e32 v100, 0, v105
	v_mul_f32_e32 v102, v102, v102
	v_mul_f32_e32 v98, v98, v98
	v_mul_f32_e32 v99, v99, v99
	v_mul_f32_e32 v100, v100, v100
	v_mul_f32_e32 v101, v101, v101
	v_cvt_pk_bf16_f32 v98, v102, v98
	v_cvt_pk_bf16_f32 v99, v99, v100
	v_cvt_pk_bf16_f32 v100, v106, v103
	v_cvt_pk_bf16_f32 v101, v104, v101
	v_add_u32_e32 v103, 0x20100, v145
	global_store_dwordx4 v103, v[98:101], s[42:43]
	s_waitcnt lgkmcnt(0)
	v_pk_mul_f32 v[90:91], v[90:91], v[154:155] op_sel_hi:[1,0]
	v_pk_mul_f32 v[94:95], v[94:95], v[154:155] op_sel_hi:[1,0]
	v_pk_mul_f32 v[92:93], v[92:93], v[154:155] op_sel_hi:[1,0]
	v_max_f32_e32 v90, 0, v90
	v_pk_mul_f32 v[96:97], v[96:97], v[154:155] op_sel_hi:[1,0]
	v_mul_f32_e32 v99, v90, v90
	v_max_f32_e32 v90, 0, v95
	v_max_f32_e32 v91, 0, v91
	v_max_f32_e32 v92, 0, v92
	v_max_f32_e32 v94, 0, v94
	v_mul_f32_e32 v90, v90, v90
	v_mul_f32_e32 v95, v91, v91
	v_max_f32_e32 v91, 0, v96
	v_mul_f32_e32 v96, v92, v92
	v_max_f32_e32 v92, 0, v97
	v_max_f32_e32 v93, 0, v93
	v_pk_mul_f32 v[84:85], v[84:85], v[154:155] op_sel_hi:[1,0]
	v_pk_mul_f32 v[82:83], v[82:83], v[154:155] op_sel_hi:[1,0]
	v_add_u32_e32 v98, 0x40000, v145
	v_mul_f32_e32 v94, v94, v94
	v_mul_f32_e32 v91, v91, v91
	v_mul_f32_e32 v92, v92, v92
	v_mul_f32_e32 v93, v93, v93
	v_cvt_pk_bf16_f32 v90, v94, v90
	v_pk_mul_f32 v[88:89], v[88:89], v[154:155] op_sel_hi:[1,0]
	v_pk_mul_f32 v[86:87], v[86:87], v[154:155] op_sel_hi:[1,0]
	v_max_f32_e32 v82, 0, v82
	v_max_f32_e32 v83, 0, v83
	v_max_f32_e32 v84, 0, v84
	v_cvt_pk_bf16_f32 v91, v91, v92
	v_cvt_pk_bf16_f32 v92, v99, v95
	v_cvt_pk_bf16_f32 v93, v96, v93
	global_store_dwordx4 v98, v[90:93], s[42:43]
	v_max_f32_e32 v86, 0, v86
	v_max_f32_e32 v85, 0, v85
	v_mul_f32_e32 v90, v82, v82
	v_max_f32_e32 v82, 0, v87
	v_mul_f32_e32 v87, v83, v83
	v_max_f32_e32 v83, 0, v88
	v_mul_f32_e32 v88, v84, v84
	v_max_f32_e32 v84, 0, v89
	v_mul_f32_e32 v86, v86, v86
	v_mul_f32_e32 v82, v82, v82
	v_mul_f32_e32 v83, v83, v83
	v_mul_f32_e32 v84, v84, v84
	v_mul_f32_e32 v85, v85, v85
	v_cvt_pk_bf16_f32 v82, v86, v82
	v_cvt_pk_bf16_f32 v83, v83, v84
	v_cvt_pk_bf16_f32 v84, v90, v87
	v_cvt_pk_bf16_f32 v85, v88, v85
	v_add_u32_e32 v87, 0x40100, v145
	global_store_dwordx4 v87, v[82:85], s[42:43]
	s_waitcnt lgkmcnt(0)
	v_pk_mul_f32 v[74:75], v[74:75], v[156:157] op_sel_hi:[1,0]
	v_pk_mul_f32 v[78:79], v[78:79], v[156:157] op_sel_hi:[1,0]
	v_pk_mul_f32 v[76:77], v[76:77], v[156:157] op_sel_hi:[1,0]
	v_max_f32_e32 v74, 0, v74
	v_pk_mul_f32 v[80:81], v[80:81], v[156:157] op_sel_hi:[1,0]
	v_mul_f32_e32 v83, v74, v74
	v_max_f32_e32 v74, 0, v79
	v_max_f32_e32 v75, 0, v75
	v_max_f32_e32 v76, 0, v76
	v_max_f32_e32 v78, 0, v78
	v_mul_f32_e32 v74, v74, v74
	v_mul_f32_e32 v79, v75, v75
	v_max_f32_e32 v75, 0, v80
	v_mul_f32_e32 v80, v76, v76
	v_max_f32_e32 v76, 0, v81
	v_max_f32_e32 v77, 0, v77
	v_pk_mul_f32 v[68:69], v[68:69], v[156:157] op_sel_hi:[1,0]
	v_pk_mul_f32 v[66:67], v[66:67], v[156:157] op_sel_hi:[1,0]
	v_add_u32_e32 v82, 0x60000, v145
	v_mul_f32_e32 v78, v78, v78
	v_mul_f32_e32 v75, v75, v75
	v_mul_f32_e32 v76, v76, v76
	v_mul_f32_e32 v77, v77, v77
	v_cvt_pk_bf16_f32 v74, v78, v74
	v_pk_mul_f32 v[72:73], v[72:73], v[156:157] op_sel_hi:[1,0]
	v_pk_mul_f32 v[70:71], v[70:71], v[156:157] op_sel_hi:[1,0]
	v_max_f32_e32 v66, 0, v66
	v_max_f32_e32 v67, 0, v67
	v_max_f32_e32 v68, 0, v68
	v_cvt_pk_bf16_f32 v75, v75, v76
	v_cvt_pk_bf16_f32 v76, v83, v79
	v_cvt_pk_bf16_f32 v77, v80, v77
	global_store_dwordx4 v82, v[74:77], s[42:43]
	v_max_f32_e32 v70, 0, v70
	v_max_f32_e32 v69, 0, v69
	v_mul_f32_e32 v74, v66, v66
	v_max_f32_e32 v66, 0, v71
	v_mul_f32_e32 v71, v67, v67
	v_max_f32_e32 v67, 0, v72
	v_mul_f32_e32 v72, v68, v68
	v_max_f32_e32 v68, 0, v73
	v_mul_f32_e32 v70, v70, v70
	v_mul_f32_e32 v66, v66, v66
	v_mul_f32_e32 v67, v67, v67
	v_mul_f32_e32 v68, v68, v68
	v_mul_f32_e32 v69, v69, v69
	v_cvt_pk_bf16_f32 v66, v70, v66
	v_cvt_pk_bf16_f32 v67, v67, v68
	v_cvt_pk_bf16_f32 v68, v74, v71
	v_cvt_pk_bf16_f32 v69, v72, v69
	v_add_u32_e32 v71, 0x60100, v145
	global_store_dwordx4 v71, v[66:69], s[42:43]
	s_waitcnt lgkmcnt(0)
	v_pk_mul_f32 v[58:59], v[58:59], v[158:159] op_sel_hi:[1,0]
	v_pk_mul_f32 v[62:63], v[62:63], v[158:159] op_sel_hi:[1,0]
	v_pk_mul_f32 v[60:61], v[60:61], v[158:159] op_sel_hi:[1,0]
	v_max_f32_e32 v58, 0, v58
	v_pk_mul_f32 v[64:65], v[64:65], v[158:159] op_sel_hi:[1,0]
	v_mul_f32_e32 v67, v58, v58
	v_max_f32_e32 v58, 0, v63
	v_max_f32_e32 v59, 0, v59
	v_max_f32_e32 v60, 0, v60
	v_max_f32_e32 v62, 0, v62
	v_mul_f32_e32 v58, v58, v58
	v_mul_f32_e32 v63, v59, v59
	v_max_f32_e32 v59, 0, v64
	v_mul_f32_e32 v64, v60, v60
	v_max_f32_e32 v60, 0, v65
	v_max_f32_e32 v61, 0, v61
	v_pk_mul_f32 v[52:53], v[52:53], v[158:159] op_sel_hi:[1,0]
	v_pk_mul_f32 v[50:51], v[50:51], v[158:159] op_sel_hi:[1,0]
	v_add_u32_e32 v66, 0x100000, v145
	v_mul_f32_e32 v62, v62, v62
	v_mul_f32_e32 v59, v59, v59
	v_mul_f32_e32 v60, v60, v60
	v_mul_f32_e32 v61, v61, v61
	v_cvt_pk_bf16_f32 v58, v62, v58
	v_pk_mul_f32 v[56:57], v[56:57], v[158:159] op_sel_hi:[1,0]
	v_pk_mul_f32 v[54:55], v[54:55], v[158:159] op_sel_hi:[1,0]
	v_max_f32_e32 v50, 0, v50
	v_max_f32_e32 v51, 0, v51
	v_max_f32_e32 v52, 0, v52
	v_cvt_pk_bf16_f32 v59, v59, v60
	v_cvt_pk_bf16_f32 v60, v67, v63
	v_cvt_pk_bf16_f32 v61, v64, v61
	global_store_dwordx4 v66, v[58:61], s[42:43]
	v_max_f32_e32 v54, 0, v54
	v_max_f32_e32 v53, 0, v53
	v_mul_f32_e32 v58, v50, v50
	v_max_f32_e32 v50, 0, v55
	v_mul_f32_e32 v55, v51, v51
	v_max_f32_e32 v51, 0, v56
	v_mul_f32_e32 v56, v52, v52
	v_max_f32_e32 v52, 0, v57
	v_mul_f32_e32 v54, v54, v54
	v_mul_f32_e32 v50, v50, v50
	v_mul_f32_e32 v51, v51, v51
	v_mul_f32_e32 v52, v52, v52
	v_mul_f32_e32 v53, v53, v53
	v_cvt_pk_bf16_f32 v50, v54, v50
	v_cvt_pk_bf16_f32 v51, v51, v52
	v_cvt_pk_bf16_f32 v52, v58, v55
	v_cvt_pk_bf16_f32 v53, v56, v53
	v_add_u32_e32 v55, 0x100100, v145
	global_store_dwordx4 v55, v[50:53], s[42:43]
	s_waitcnt lgkmcnt(0)
	v_pk_mul_f32 v[42:43], v[42:43], v[160:161] op_sel_hi:[1,0]
	v_pk_mul_f32 v[46:47], v[46:47], v[160:161] op_sel_hi:[1,0]
	v_pk_mul_f32 v[44:45], v[44:45], v[160:161] op_sel_hi:[1,0]
	v_max_f32_e32 v42, 0, v42
	v_pk_mul_f32 v[48:49], v[48:49], v[160:161] op_sel_hi:[1,0]
	v_mul_f32_e32 v51, v42, v42
	v_max_f32_e32 v42, 0, v47
	v_max_f32_e32 v43, 0, v43
	v_max_f32_e32 v44, 0, v44
	v_max_f32_e32 v46, 0, v46
	v_mul_f32_e32 v42, v42, v42
	v_mul_f32_e32 v47, v43, v43
	v_max_f32_e32 v43, 0, v48
	v_mul_f32_e32 v48, v44, v44
	v_max_f32_e32 v44, 0, v49
	v_max_f32_e32 v45, 0, v45
	v_pk_mul_f32 v[36:37], v[36:37], v[160:161] op_sel_hi:[1,0]
	v_pk_mul_f32 v[34:35], v[34:35], v[160:161] op_sel_hi:[1,0]
	v_add_u32_e32 v50, 0x120000, v145
	v_mul_f32_e32 v46, v46, v46
	v_mul_f32_e32 v43, v43, v43
	v_mul_f32_e32 v44, v44, v44
	v_mul_f32_e32 v45, v45, v45
	v_cvt_pk_bf16_f32 v42, v46, v42
	v_pk_mul_f32 v[40:41], v[40:41], v[160:161] op_sel_hi:[1,0]
	v_pk_mul_f32 v[38:39], v[38:39], v[160:161] op_sel_hi:[1,0]
	v_max_f32_e32 v34, 0, v34
	v_max_f32_e32 v35, 0, v35
	v_max_f32_e32 v36, 0, v36
	v_cvt_pk_bf16_f32 v43, v43, v44
	v_cvt_pk_bf16_f32 v44, v51, v47
	v_cvt_pk_bf16_f32 v45, v48, v45
	global_store_dwordx4 v50, v[42:45], s[42:43]
	v_max_f32_e32 v38, 0, v38
	v_max_f32_e32 v37, 0, v37
	v_mul_f32_e32 v42, v34, v34
	v_max_f32_e32 v34, 0, v39
	v_mul_f32_e32 v39, v35, v35
	v_max_f32_e32 v35, 0, v40
	v_mul_f32_e32 v40, v36, v36
	v_max_f32_e32 v36, 0, v41
	v_mul_f32_e32 v38, v38, v38
	v_mul_f32_e32 v34, v34, v34
	v_mul_f32_e32 v35, v35, v35
	v_mul_f32_e32 v36, v36, v36
	v_mul_f32_e32 v37, v37, v37
	v_cvt_pk_bf16_f32 v34, v38, v34
	v_cvt_pk_bf16_f32 v35, v35, v36
	v_cvt_pk_bf16_f32 v36, v42, v39
	v_cvt_pk_bf16_f32 v37, v40, v37
	v_add_u32_e32 v39, 0x120100, v145
	global_store_dwordx4 v39, v[34:37], s[42:43]
	s_waitcnt lgkmcnt(0)
	v_pk_mul_f32 v[24:25], v[24:25], v[162:163] op_sel_hi:[1,0]
	v_pk_mul_f32 v[28:29], v[28:29], v[162:163] op_sel_hi:[1,0]
	v_pk_mul_f32 v[26:27], v[26:27], v[162:163] op_sel_hi:[1,0]
	v_max_f32_e32 v24, 0, v24
	v_pk_mul_f32 v[30:31], v[30:31], v[162:163] op_sel_hi:[1,0]
	v_mul_f32_e32 v35, v24, v24
	v_max_f32_e32 v24, 0, v29
	v_max_f32_e32 v25, 0, v25
	v_max_f32_e32 v26, 0, v26
	v_max_f32_e32 v28, 0, v28
	v_mul_f32_e32 v24, v24, v24
	v_mul_f32_e32 v29, v25, v25
	v_max_f32_e32 v25, 0, v30
	v_mul_f32_e32 v30, v26, v26
	v_max_f32_e32 v26, 0, v31
	v_max_f32_e32 v27, 0, v27
	v_pk_mul_f32 v[18:19], v[18:19], v[162:163] op_sel_hi:[1,0]
	v_pk_mul_f32 v[16:17], v[16:17], v[162:163] op_sel_hi:[1,0]
	v_add_u32_e32 v34, 0x140000, v145
	v_mul_f32_e32 v28, v28, v28
	v_mul_f32_e32 v25, v25, v25
	v_mul_f32_e32 v26, v26, v26
	v_mul_f32_e32 v27, v27, v27
	v_cvt_pk_bf16_f32 v24, v28, v24
	v_pk_mul_f32 v[22:23], v[22:23], v[162:163] op_sel_hi:[1,0]
	v_pk_mul_f32 v[20:21], v[20:21], v[162:163] op_sel_hi:[1,0]
	v_max_f32_e32 v16, 0, v16
	v_max_f32_e32 v17, 0, v17
	v_max_f32_e32 v18, 0, v18
	v_cvt_pk_bf16_f32 v25, v25, v26
	v_cvt_pk_bf16_f32 v26, v35, v29
	v_cvt_pk_bf16_f32 v27, v30, v27
	global_store_dwordx4 v34, v[24:27], s[42:43]
	v_max_f32_e32 v20, 0, v20
	v_max_f32_e32 v19, 0, v19
	v_mul_f32_e32 v24, v16, v16
	v_max_f32_e32 v16, 0, v21
	v_mul_f32_e32 v21, v17, v17
	v_max_f32_e32 v17, 0, v22
	v_mul_f32_e32 v22, v18, v18
	v_max_f32_e32 v18, 0, v23
	v_mul_f32_e32 v20, v20, v20
	v_mul_f32_e32 v16, v16, v16
	v_mul_f32_e32 v17, v17, v17
	v_mul_f32_e32 v18, v18, v18
	v_mul_f32_e32 v19, v19, v19
	v_cvt_pk_bf16_f32 v16, v20, v16
	v_cvt_pk_bf16_f32 v17, v17, v18
	v_cvt_pk_bf16_f32 v18, v24, v21
	v_cvt_pk_bf16_f32 v19, v22, v19
	v_add_u32_e32 v21, 0x140100, v145
	global_store_dwordx4 v21, v[16:19], s[42:43]
	s_waitcnt lgkmcnt(0)
	v_pk_mul_f32 v[8:9], v[8:9], v[164:165] op_sel_hi:[1,0]
	v_pk_mul_f32 v[12:13], v[12:13], v[164:165] op_sel_hi:[1,0]
	v_pk_mul_f32 v[10:11], v[10:11], v[164:165] op_sel_hi:[1,0]
	v_max_f32_e32 v8, 0, v8
	v_pk_mul_f32 v[14:15], v[14:15], v[164:165] op_sel_hi:[1,0]
	v_mul_f32_e32 v17, v8, v8
	v_max_f32_e32 v8, 0, v13
	v_max_f32_e32 v9, 0, v9
	v_max_f32_e32 v10, 0, v10
	v_max_f32_e32 v12, 0, v12
	v_mul_f32_e32 v8, v8, v8
	v_mul_f32_e32 v13, v9, v9
	v_max_f32_e32 v9, 0, v14
	v_mul_f32_e32 v14, v10, v10
	v_max_f32_e32 v10, 0, v15
	v_max_f32_e32 v11, 0, v11
	v_pk_mul_f32 v[0:1], v[0:1], v[164:165] op_sel_hi:[1,0]
	v_add_u32_e32 v16, 0x160000, v145
	v_mul_f32_e32 v12, v12, v12
	v_mul_f32_e32 v9, v9, v9
	v_mul_f32_e32 v10, v10, v10
	v_mul_f32_e32 v11, v11, v11
	v_cvt_pk_bf16_f32 v8, v12, v8
	v_pk_mul_f32 v[4:5], v[4:5], v[164:165] op_sel_hi:[1,0]
	v_pk_mul_f32 v[2:3], v[2:3], v[164:165] op_sel_hi:[1,0]
	v_max_f32_e32 v0, 0, v0
	v_cvt_pk_bf16_f32 v9, v9, v10
	v_cvt_pk_bf16_f32 v10, v17, v13
	v_cvt_pk_bf16_f32 v11, v14, v11
	global_store_dwordx4 v16, v[8:11], s[42:43]
	v_pk_mul_f32 v[6:7], v[6:7], v[164:165] op_sel_hi:[1,0]
	v_max_f32_e32 v4, 0, v4
	v_mul_f32_e32 v8, v0, v0
	v_max_f32_e32 v0, 0, v5
	v_max_f32_e32 v1, 0, v1
	v_max_f32_e32 v2, 0, v2
	v_mul_f32_e32 v4, v4, v4
	v_mul_f32_e32 v0, v0, v0
	v_mul_f32_e32 v5, v1, v1
	v_max_f32_e32 v1, 0, v6
	v_mul_f32_e32 v6, v2, v2
	v_max_f32_e32 v2, 0, v7
	v_max_f32_e32 v3, 0, v3
	v_mul_f32_e32 v1, v1, v1
	v_mul_f32_e32 v2, v2, v2
	v_mul_f32_e32 v3, v3, v3
	v_cvt_pk_bf16_f32 v0, v4, v0
	v_add_u32_e32 v4, 0x160100, v145
	v_cvt_pk_bf16_f32 v1, v1, v2
	v_cvt_pk_bf16_f32 v2, v8, v5
	v_cvt_pk_bf16_f32 v3, v6, v3
	global_store_dwordx4 v4, v[0:3], s[42:43]
	s_cbranch_vccnz .LBB0_1189
	s_andn2_b64 vcc, exec, s[0:1]
	s_cbranch_vccnz .LBB0_1188
	s_barrier
	s_branch .LBB0_1188
